# P1 tail half-unit K-loop: three-buffer ring (K-tile staged two ahead) using the unused A-half slots plus 16 KiB above the ring
# speedup vs baseline: 1.0069x; 1.0011x over previous
.LBB0_104:
	s_ashr_i32 s65, s64, 31
	s_lshl_b64 s[2:3], s[64:65], 19
	s_add_u32 s2, s80, s2
	s_addc_u32 s3, s81, s3
	s_cmp_gt_i32 s42, 0
	s_cselect_b32 s4, 0x40000, 0
	s_add_u32 s68, s2, s4
	s_addc_u32 s69, s3, 0
	s_and_b64 s[2:3], s[66:67], exec
	s_cselect_b32 s4, s69, s77
	s_cselect_b32 s43, s68, s76
	s_ashr_i32 s63, s62, 31
	s_lshl_b64 s[2:3], s[62:63], 19
	s_add_u32 s70, s10, s2
	s_addc_u32 s71, s11, s3
	s_and_b64 s[2:3], s[66:67], exec
	s_cselect_b32 s63, s71, s1
	s_cselect_b32 s65, s70, s0
	s_cmp_lt_i32 s33, 0
	v_mov_b32_e32 v4, v2
	v_mov_b32_e32 v5, v2
	s_cselect_b64 s[86:87], -1, 0
	s_add_u32 s36, s0, 0x100
	v_mov_b32_e32 v3, v2
	v_mov_b32_e32 v86, 0
	v_mov_b64_e32 v[24:25], v[4:5]
	v_mov_b64_e32 v[56:57], v[4:5]
	v_mov_b64_e32 v[28:29], v[4:5]
	v_mov_b64_e32 v[60:61], v[4:5]
	v_mov_b64_e32 v[36:37], v[4:5]
	v_mov_b64_e32 v[68:69], v[4:5]
	v_mov_b64_e32 v[32:33], v[4:5]
	v_mov_b64_e32 v[64:65], v[4:5]
	v_mov_b64_e32 v[12:13], v[4:5]
	v_mov_b64_e32 v[44:45], v[4:5]
	v_mov_b64_e32 v[16:17], v[4:5]
	v_mov_b64_e32 v[48:49], v[4:5]
	v_mov_b64_e32 v[20:21], v[4:5]
	v_mov_b64_e32 v[52:53], v[4:5]
	v_mov_b64_e32 v[8:9], v[4:5]
	v_mov_b64_e32 v[40:41], v[4:5]
	s_addc_u32 s44, s1, 0
	s_mov_b32 s45, -2
	v_mov_b64_e32 v[22:23], v[2:3]
	v_mov_b64_e32 v[54:55], v[2:3]
	v_mov_b64_e32 v[26:27], v[2:3]
	v_mov_b64_e32 v[58:59], v[2:3]
	v_mov_b64_e32 v[34:35], v[2:3]
	v_mov_b64_e32 v[66:67], v[2:3]
	v_mov_b64_e32 v[30:31], v[2:3]
	v_mov_b64_e32 v[62:63], v[2:3]
	v_mov_b64_e32 v[10:11], v[2:3]
	v_mov_b64_e32 v[42:43], v[2:3]
	v_mov_b64_e32 v[14:15], v[2:3]
	v_mov_b64_e32 v[46:47], v[2:3]
	v_mov_b64_e32 v[18:19], v[2:3]
	v_mov_b64_e32 v[50:51], v[2:3]
	v_mov_b64_e32 v[6:7], v[2:3]
	v_mov_b64_e32 v[38:39], v[2:3]
	v_mov_b32_e32 v87, v86
	v_mov_b32_e32 v88, v86
	v_mov_b32_e32 v89, v86
	v_mov_b32_e32 v118, v86
	v_mov_b32_e32 v119, v86
	v_mov_b32_e32 v120, v86
	v_mov_b32_e32 v121, v86
	v_mov_b32_e32 v90, v86
	v_mov_b32_e32 v91, v86
	v_mov_b32_e32 v92, v86
	v_mov_b32_e32 v93, v86
	v_mov_b32_e32 v122, v86
	v_mov_b32_e32 v123, v86
	v_mov_b32_e32 v124, v86
	v_mov_b32_e32 v125, v86
	v_mov_b32_e32 v94, v86
	v_mov_b32_e32 v95, v86
	v_mov_b32_e32 v96, v86
	v_mov_b32_e32 v97, v86
	v_mov_b32_e32 v126, v86
	v_mov_b32_e32 v127, v86
	v_mov_b32_e32 v128, v86
	v_mov_b32_e32 v129, v86
	v_mov_b32_e32 v98, v86
	v_mov_b32_e32 v99, v86
	v_mov_b32_e32 v100, v86
	v_mov_b32_e32 v101, v86
	v_mov_b32_e32 v130, v86
	v_mov_b32_e32 v131, v86
	v_mov_b32_e32 v132, v86
	v_mov_b32_e32 v133, v86
	v_mov_b32_e32 v74, v86
	v_mov_b32_e32 v75, v86
	v_mov_b32_e32 v76, v86
	v_mov_b32_e32 v77, v86
	v_mov_b32_e32 v106, v86
	v_mov_b32_e32 v107, v86
	v_mov_b32_e32 v108, v86
	v_mov_b32_e32 v109, v86
	v_mov_b32_e32 v78, v86
	v_mov_b32_e32 v79, v86
	v_mov_b32_e32 v80, v86
	v_mov_b32_e32 v81, v86
	v_mov_b32_e32 v110, v86
	v_mov_b32_e32 v111, v86
	v_mov_b32_e32 v112, v86
	v_mov_b32_e32 v113, v86
	v_mov_b32_e32 v82, v86
	v_mov_b32_e32 v83, v86
	v_mov_b32_e32 v84, v86
	v_mov_b32_e32 v85, v86
	v_mov_b32_e32 v114, v86
	v_mov_b32_e32 v115, v86
	v_mov_b32_e32 v116, v86
	v_mov_b32_e32 v117, v86
	v_mov_b32_e32 v70, v86
	v_mov_b32_e32 v71, v86
	v_mov_b32_e32 v72, v86
	v_mov_b32_e32 v73, v86
	v_mov_b32_e32 v102, v86
	v_mov_b32_e32 v103, v86
	v_mov_b32_e32 v104, v86
	v_mov_b32_e32 v105, v86
	s_and_b64 vcc, exec, s[86:87]
	s_cbranch_vccnz .LBB0_107
	s_add_u32 s2, s0, 0x100
	s_addc_u32 s3, s1, 0
	s_add_u32 s84, s76, 0x100
	s_addc_u32 s85, s77, 0
	s_mov_b32 s45, 0
	s_waitcnt vmcnt(0)
	s_and_b64 vcc, exec, s[14:15]
	s_cbranch_vccnz .Lhu_loop
	v_lshl_add_u64 v[6:7], s[2:3], 0, v[208:209]
	v_lshl_add_u64 v[8:9], s[2:3], 0, v[212:213]
	s_add_u32 s88, s2, 0x40000
	s_addc_u32 s89, s3, 0
	v_lshl_add_u64 v[10:11], s[88:89], 0, v[208:209]
	v_lshl_add_u64 v[12:13], s[88:89], 0, v[212:213]
	v_lshl_add_u64 v[14:15], s[84:85], 0, v[206:207]
	v_lshl_add_u64 v[16:17], s[84:85], 0, v[210:211]
	s_add_u32 s2, s2, 0x80
	s_addc_u32 s3, s3, 0
	s_add_u32 s84, s84, 0x80
	s_addc_u32 s85, s85, 0
	s_add_i32 m0, s61, 0xc000
	s_nop 0
	global_load_lds_dwordx4 v[6:7], off
	s_add_i32 m0, s61, 0xe000
	s_nop 0
	global_load_lds_dwordx4 v[8:9], off
	s_add_i32 m0, s61, 0x20000
	s_nop 0
	global_load_lds_dwordx4 v[10:11], off
	s_add_i32 m0, s61, 0x22000
	s_nop 0
	global_load_lds_dwordx4 v[12:13], off
	s_mov_b32 m0, s95
	s_nop 0
	global_load_lds_dwordx4 v[14:15], off
	s_mov_b32 m0, s96
	s_nop 0
	global_load_lds_dwordx4 v[16:17], off
.Lhu_loop:
	ds_read_b128 v[150:153], v248
	ds_read_b128 v[154:157], v248 offset:1024
	ds_read_b128 v[158:161], v248 offset:2048
	ds_read_b128 v[162:165], v248 offset:3072
	ds_read_b128 v[134:137], v249
	ds_read_b128 v[138:141], v249 offset:1024
	ds_read_b128 v[142:145], v249 offset:2048
	ds_read_b128 v[146:149], v249 offset:3072
	ds_read_b128 v[166:169], v250
	ds_read_b128 v[170:173], v250 offset:1024
	ds_read_b128 v[174:177], v250 offset:2048
	ds_read_b128 v[178:181], v250 offset:3072
	ds_read_b128 v[182:185], v250 offset:4096
	ds_read_b128 v[186:189], v250 offset:5120
	ds_read_b128 v[190:193], v250 offset:6144
	ds_read_b128 v[194:197], v250 offset:7168
	s_and_b64 vcc, exec, s[14:15]
	s_cbranch_vccz .Lhu_k1_y
	v_lshl_add_u64 v[6:7], s[2:3], 0, v[208:209]
	v_lshl_add_u64 v[8:9], s[2:3], 0, v[212:213]
	s_add_u32 s88, s2, 0x40000
	s_addc_u32 s89, s3, 0
	v_lshl_add_u64 v[10:11], s[88:89], 0, v[208:209]
	v_lshl_add_u64 v[12:13], s[88:89], 0, v[212:213]
	v_lshl_add_u64 v[14:15], s[84:85], 0, v[206:207]
	v_lshl_add_u64 v[16:17], s[84:85], 0, v[210:211]
	s_add_u32 s2, s2, 0x80
	s_addc_u32 s3, s3, 0
	s_add_u32 s84, s84, 0x80
	s_addc_u32 s85, s85, 0
	s_add_i32 m0, s61, 0xc000
	s_nop 0
	global_load_lds_dwordx4 v[6:7], off
	s_add_i32 m0, s61, 0xe000
	s_nop 0
	global_load_lds_dwordx4 v[8:9], off
	s_add_i32 m0, s61, 0x20000
	s_nop 0
	global_load_lds_dwordx4 v[10:11], off
	s_add_i32 m0, s61, 0x22000
	s_nop 0
	global_load_lds_dwordx4 v[12:13], off
	s_mov_b32 m0, s95
	s_nop 0
	global_load_lds_dwordx4 v[14:15], off
	s_mov_b32 m0, s96
	s_nop 0
	global_load_lds_dwordx4 v[16:17], off
	s_branch .Lhu_k1_bar

.Lhu_k1_bar:
	s_waitcnt lgkmcnt(0)
	s_barrier
	s_and_b64 vcc, exec, s[14:15]
	s_cbranch_vccnz .Lhu_k1_x
	v_lshl_add_u64 v[6:7], s[2:3], 0, v[208:209]
	v_lshl_add_u64 v[8:9], s[2:3], 0, v[212:213]
	s_add_u32 s88, s2, 0x40000
	s_addc_u32 s89, s3, 0
	v_lshl_add_u64 v[10:11], s[88:89], 0, v[208:209]
	v_lshl_add_u64 v[12:13], s[88:89], 0, v[212:213]
	v_lshl_add_u64 v[14:15], s[84:85], 0, v[206:207]
	v_lshl_add_u64 v[16:17], s[84:85], 0, v[210:211]
	s_add_u32 s2, s2, 0x80
	s_addc_u32 s3, s3, 0
	s_add_u32 s84, s84, 0x80
	s_addc_u32 s85, s85, 0
	s_mov_b32 m0, s73
	s_nop 0
	global_load_lds_dwordx4 v[6:7], off
	s_mov_b32 m0, s75
	s_nop 0
	global_load_lds_dwordx4 v[8:9], off
	s_mov_b32 m0, s92
	s_nop 0
	global_load_lds_dwordx4 v[10:11], off
	s_mov_b32 m0, s93
	s_nop 0
	global_load_lds_dwordx4 v[12:13], off
	s_mov_b32 m0, s61
	s_nop 0
	global_load_lds_dwordx4 v[14:15], off
	s_mov_b32 m0, s94
	s_nop 0
	global_load_lds_dwordx4 v[16:17], off

.Lhu_k1_x:
	s_setprio 1
	v_mfma_f32_16x16x32_bf16 v[102:105], v[150:153], v[166:169], v[102:105]
	v_mfma_f32_16x16x32_bf16 v[70:73], v[158:161], v[166:169], v[70:73]
	v_mfma_f32_16x16x32_bf16 v[114:117], v[150:153], v[174:177], v[114:117]
	v_mfma_f32_16x16x32_bf16 v[82:85], v[158:161], v[174:177], v[82:85]
	v_mfma_f32_16x16x32_bf16 v[110:113], v[150:153], v[182:185], v[110:113]
	v_mfma_f32_16x16x32_bf16 v[78:81], v[158:161], v[182:185], v[78:81]
	v_mfma_f32_16x16x32_bf16 v[106:109], v[150:153], v[190:193], v[106:109]
	v_mfma_f32_16x16x32_bf16 v[74:77], v[158:161], v[190:193], v[74:77]
	v_mfma_f32_16x16x32_bf16 v[102:105], v[154:157], v[170:173], v[102:105]
	v_mfma_f32_16x16x32_bf16 v[70:73], v[162:165], v[170:173], v[70:73]
	v_mfma_f32_16x16x32_bf16 v[114:117], v[154:157], v[178:181], v[114:117]
	v_mfma_f32_16x16x32_bf16 v[82:85], v[162:165], v[178:181], v[82:85]
	v_mfma_f32_16x16x32_bf16 v[110:113], v[154:157], v[186:189], v[110:113]
	v_mfma_f32_16x16x32_bf16 v[78:81], v[162:165], v[186:189], v[78:81]
	v_mfma_f32_16x16x32_bf16 v[106:109], v[154:157], v[194:197], v[106:109]
	v_mfma_f32_16x16x32_bf16 v[74:77], v[162:165], v[194:197], v[74:77]
	s_setprio 0
	s_setprio 1
	v_mfma_f32_16x16x32_bf16 v[130:133], v[134:137], v[166:169], v[130:133]
	v_mfma_f32_16x16x32_bf16 v[98:101], v[142:145], v[166:169], v[98:101]
	v_mfma_f32_16x16x32_bf16 v[126:129], v[134:137], v[174:177], v[126:129]
	v_mfma_f32_16x16x32_bf16 v[94:97], v[142:145], v[174:177], v[94:97]
	v_mfma_f32_16x16x32_bf16 v[122:125], v[134:137], v[182:185], v[122:125]
	v_mfma_f32_16x16x32_bf16 v[90:93], v[142:145], v[182:185], v[90:93]
	v_mfma_f32_16x16x32_bf16 v[118:121], v[134:137], v[190:193], v[118:121]
	v_mfma_f32_16x16x32_bf16 v[86:89], v[142:145], v[190:193], v[86:89]
	v_mfma_f32_16x16x32_bf16 v[130:133], v[138:141], v[170:173], v[130:133]
	v_mfma_f32_16x16x32_bf16 v[98:101], v[146:149], v[170:173], v[98:101]
	v_mfma_f32_16x16x32_bf16 v[126:129], v[138:141], v[178:181], v[126:129]
	v_mfma_f32_16x16x32_bf16 v[94:97], v[146:149], v[178:181], v[94:97]
	v_mfma_f32_16x16x32_bf16 v[122:125], v[138:141], v[186:189], v[122:125]
	v_mfma_f32_16x16x32_bf16 v[90:93], v[146:149], v[186:189], v[90:93]
	v_mfma_f32_16x16x32_bf16 v[118:121], v[138:141], v[194:197], v[118:121]
	v_mfma_f32_16x16x32_bf16 v[86:89], v[146:149], v[194:197], v[86:89]
	s_setprio 0
	s_waitcnt vmcnt(6)
.Lhu_k1_cb:
	s_barrier
	v_add_u32_e32 v3, 0x18000, v247
	v_add_u32_e32 v4, 0x1c000, v247
	ds_read_b128 v[150:153], v3
	ds_read_b128 v[154:157], v3 offset:1024
	ds_read_b128 v[158:161], v3 offset:2048
	ds_read_b128 v[162:165], v3 offset:3072
	ds_read_b128 v[134:137], v4
	ds_read_b128 v[138:141], v4 offset:1024
	ds_read_b128 v[142:145], v4 offset:2048
	ds_read_b128 v[146:149], v4 offset:3072
	ds_read_b128 v[166:169], v250 offset:32768
	ds_read_b128 v[170:173], v250 offset:33792
	ds_read_b128 v[174:177], v250 offset:34816
	ds_read_b128 v[178:181], v250 offset:35840
	ds_read_b128 v[182:185], v250 offset:36864
	ds_read_b128 v[186:189], v250 offset:37888
	ds_read_b128 v[190:193], v250 offset:38912
	ds_read_b128 v[194:197], v250 offset:39936
	s_and_b64 vcc, exec, s[14:15]
	s_cbranch_vccz .Lhu_k2_y
	v_lshl_add_u64 v[6:7], s[2:3], 0, v[208:209]
	v_lshl_add_u64 v[8:9], s[2:3], 0, v[212:213]
	s_add_u32 s88, s2, 0x40000
	s_addc_u32 s89, s3, 0
	v_lshl_add_u64 v[10:11], s[88:89], 0, v[208:209]
	v_lshl_add_u64 v[12:13], s[88:89], 0, v[212:213]
	v_lshl_add_u64 v[14:15], s[84:85], 0, v[206:207]
	v_lshl_add_u64 v[16:17], s[84:85], 0, v[210:211]
	s_add_u32 s2, s2, 0x80
	s_addc_u32 s3, s3, 0
	s_add_u32 s84, s84, 0x80
	s_addc_u32 s85, s85, 0
	s_mov_b32 m0, s73
	s_nop 0
	global_load_lds_dwordx4 v[6:7], off
	s_mov_b32 m0, s75
	s_nop 0
	global_load_lds_dwordx4 v[8:9], off
	s_mov_b32 m0, s92
	s_nop 0
	global_load_lds_dwordx4 v[10:11], off
	s_mov_b32 m0, s93
	s_nop 0
	global_load_lds_dwordx4 v[12:13], off
	s_mov_b32 m0, s61
	s_nop 0
	global_load_lds_dwordx4 v[14:15], off
	s_mov_b32 m0, s94
	s_nop 0
	global_load_lds_dwordx4 v[16:17], off
	s_branch .Lhu_k2_bar

.Lhu_k2_bar:
	s_waitcnt lgkmcnt(0)
	s_barrier
	s_and_b64 vcc, exec, s[14:15]
	s_cbranch_vccnz .Lhu_k2_x
	s_cmp_eq_u32 s45, 12
	s_cbranch_scc1 .Lhu_k2_ym
	v_lshl_add_u64 v[6:7], s[2:3], 0, v[208:209]
	v_lshl_add_u64 v[8:9], s[2:3], 0, v[212:213]
	s_add_u32 s88, s2, 0x40000
	s_addc_u32 s89, s3, 0
	v_lshl_add_u64 v[10:11], s[88:89], 0, v[208:209]
	v_lshl_add_u64 v[12:13], s[88:89], 0, v[212:213]
	v_lshl_add_u64 v[14:15], s[84:85], 0, v[206:207]
	v_lshl_add_u64 v[16:17], s[84:85], 0, v[210:211]
	s_add_u32 s2, s2, 0x80
	s_addc_u32 s3, s3, 0
	s_add_u32 s84, s84, 0x80
	s_addc_u32 s85, s85, 0
	s_mov_b32 m0, s54
	s_nop 0
	global_load_lds_dwordx4 v[6:7], off
	s_mov_b32 m0, s55
	s_nop 0
	global_load_lds_dwordx4 v[8:9], off
	s_mov_b32 m0, s59
	s_nop 0
	global_load_lds_dwordx4 v[10:11], off
	s_mov_b32 m0, s24
	s_nop 0
	global_load_lds_dwordx4 v[12:13], off
	s_mov_b32 m0, s57
	s_nop 0
	global_load_lds_dwordx4 v[14:15], off
	s_mov_b32 m0, s58
	s_nop 0
	global_load_lds_dwordx4 v[16:17], off

.Lhu_k2_cb:
	s_barrier
	v_add_u32_e32 v3, 0xc000, v247
	v_add_u32_e32 v4, 0x20000, v247
	ds_read_b128 v[150:153], v3
	ds_read_b128 v[154:157], v3 offset:1024
	ds_read_b128 v[158:161], v3 offset:2048
	ds_read_b128 v[162:165], v3 offset:3072
	ds_read_b128 v[134:137], v4
	ds_read_b128 v[138:141], v4 offset:1024
	ds_read_b128 v[142:145], v4 offset:2048
	ds_read_b128 v[146:149], v4 offset:3072
	ds_read_b128 v[166:169], v250 offset:16384
	ds_read_b128 v[170:173], v250 offset:17408
	ds_read_b128 v[174:177], v250 offset:18432
	ds_read_b128 v[178:181], v250 offset:19456
	ds_read_b128 v[182:185], v250 offset:20480
	ds_read_b128 v[186:189], v250 offset:21504
	ds_read_b128 v[190:193], v250 offset:22528
	ds_read_b128 v[194:197], v250 offset:23552
	s_and_b64 vcc, exec, s[14:15]
	s_cbranch_vccz .Lhu_k3_y
	s_cmp_eq_u32 s45, 12
	s_cbranch_scc1 .Lhu_k3_bar
	v_lshl_add_u64 v[6:7], s[2:3], 0, v[208:209]
	v_lshl_add_u64 v[8:9], s[2:3], 0, v[212:213]
	s_add_u32 s88, s2, 0x40000
	s_addc_u32 s89, s3, 0
	v_lshl_add_u64 v[10:11], s[88:89], 0, v[208:209]
	v_lshl_add_u64 v[12:13], s[88:89], 0, v[212:213]
	v_lshl_add_u64 v[14:15], s[84:85], 0, v[206:207]
	v_lshl_add_u64 v[16:17], s[84:85], 0, v[210:211]
	s_add_u32 s2, s2, 0x80
	s_addc_u32 s3, s3, 0
	s_add_u32 s84, s84, 0x80
	s_addc_u32 s85, s85, 0
	s_mov_b32 m0, s54
	s_nop 0
	global_load_lds_dwordx4 v[6:7], off
	s_mov_b32 m0, s55
	s_nop 0
	global_load_lds_dwordx4 v[8:9], off
	s_mov_b32 m0, s59
	s_nop 0
	global_load_lds_dwordx4 v[10:11], off
	s_mov_b32 m0, s24
	s_nop 0
	global_load_lds_dwordx4 v[12:13], off
	s_mov_b32 m0, s57
	s_nop 0
	global_load_lds_dwordx4 v[14:15], off
	s_mov_b32 m0, s58
	s_nop 0
	global_load_lds_dwordx4 v[16:17], off
	s_branch .Lhu_k3_bar
.Lhu_k3_y:
	s_cmp_eq_u32 s45, 12
	s_cbranch_scc1 .Lhu_k3_y0
	s_waitcnt vmcnt(6)
	s_branch .Lhu_k3_bar

.Lhu_k3_bar:
	s_waitcnt lgkmcnt(0)
	s_barrier
	s_and_b64 vcc, exec, s[14:15]
	s_cbranch_vccnz .Lhu_k3_x
	s_cmp_eq_u32 s45, 12
	s_cbranch_scc1 .Lhu_k3_ym
	v_lshl_add_u64 v[6:7], s[2:3], 0, v[208:209]
	v_lshl_add_u64 v[8:9], s[2:3], 0, v[212:213]
	s_add_u32 s88, s2, 0x40000
	s_addc_u32 s89, s3, 0
	v_lshl_add_u64 v[10:11], s[88:89], 0, v[208:209]
	v_lshl_add_u64 v[12:13], s[88:89], 0, v[212:213]
	v_lshl_add_u64 v[14:15], s[84:85], 0, v[206:207]
	v_lshl_add_u64 v[16:17], s[84:85], 0, v[210:211]
	s_add_u32 s2, s2, 0x80
	s_addc_u32 s3, s3, 0
	s_add_u32 s84, s84, 0x80
	s_addc_u32 s85, s85, 0
	s_add_i32 m0, s61, 0xc000
	s_nop 0
	global_load_lds_dwordx4 v[6:7], off
	s_add_i32 m0, s61, 0xe000
	s_nop 0
	global_load_lds_dwordx4 v[8:9], off
	s_add_i32 m0, s61, 0x20000
	s_nop 0
	global_load_lds_dwordx4 v[10:11], off
	s_add_i32 m0, s61, 0x22000
	s_nop 0
	global_load_lds_dwordx4 v[12:13], off
	s_mov_b32 m0, s95
	s_nop 0
	global_load_lds_dwordx4 v[14:15], off
	s_mov_b32 m0, s96
	s_nop 0
	global_load_lds_dwordx4 v[16:17], off

.Lhu_k3_x:
	s_setprio 1
	v_mfma_f32_16x16x32_bf16 v[102:105], v[150:153], v[166:169], v[102:105]
	v_mfma_f32_16x16x32_bf16 v[70:73], v[158:161], v[166:169], v[70:73]
	v_mfma_f32_16x16x32_bf16 v[114:117], v[150:153], v[174:177], v[114:117]
	v_mfma_f32_16x16x32_bf16 v[82:85], v[158:161], v[174:177], v[82:85]
	v_mfma_f32_16x16x32_bf16 v[110:113], v[150:153], v[182:185], v[110:113]
	v_mfma_f32_16x16x32_bf16 v[78:81], v[158:161], v[182:185], v[78:81]
	v_mfma_f32_16x16x32_bf16 v[106:109], v[150:153], v[190:193], v[106:109]
	v_mfma_f32_16x16x32_bf16 v[74:77], v[158:161], v[190:193], v[74:77]
	v_mfma_f32_16x16x32_bf16 v[102:105], v[154:157], v[170:173], v[102:105]
	v_mfma_f32_16x16x32_bf16 v[70:73], v[162:165], v[170:173], v[70:73]
	v_mfma_f32_16x16x32_bf16 v[114:117], v[154:157], v[178:181], v[114:117]
	v_mfma_f32_16x16x32_bf16 v[82:85], v[162:165], v[178:181], v[82:85]
	v_mfma_f32_16x16x32_bf16 v[110:113], v[154:157], v[186:189], v[110:113]
	v_mfma_f32_16x16x32_bf16 v[78:81], v[162:165], v[186:189], v[78:81]
	v_mfma_f32_16x16x32_bf16 v[106:109], v[154:157], v[194:197], v[106:109]
	v_mfma_f32_16x16x32_bf16 v[74:77], v[162:165], v[194:197], v[74:77]
	s_setprio 0
	s_setprio 1
	v_mfma_f32_16x16x32_bf16 v[130:133], v[134:137], v[166:169], v[130:133]
	v_mfma_f32_16x16x32_bf16 v[98:101], v[142:145], v[166:169], v[98:101]
	v_mfma_f32_16x16x32_bf16 v[126:129], v[134:137], v[174:177], v[126:129]
	v_mfma_f32_16x16x32_bf16 v[94:97], v[142:145], v[174:177], v[94:97]
	v_mfma_f32_16x16x32_bf16 v[122:125], v[134:137], v[182:185], v[122:125]
	v_mfma_f32_16x16x32_bf16 v[90:93], v[142:145], v[182:185], v[90:93]
	v_mfma_f32_16x16x32_bf16 v[118:121], v[134:137], v[190:193], v[118:121]
	v_mfma_f32_16x16x32_bf16 v[86:89], v[142:145], v[190:193], v[86:89]
	v_mfma_f32_16x16x32_bf16 v[130:133], v[138:141], v[170:173], v[130:133]
	v_mfma_f32_16x16x32_bf16 v[98:101], v[146:149], v[170:173], v[98:101]
	v_mfma_f32_16x16x32_bf16 v[126:129], v[138:141], v[178:181], v[126:129]
	v_mfma_f32_16x16x32_bf16 v[94:97], v[146:149], v[178:181], v[94:97]
	v_mfma_f32_16x16x32_bf16 v[122:125], v[138:141], v[186:189], v[122:125]
	v_mfma_f32_16x16x32_bf16 v[90:93], v[146:149], v[186:189], v[90:93]
	v_mfma_f32_16x16x32_bf16 v[118:121], v[138:141], v[194:197], v[118:121]
	v_mfma_f32_16x16x32_bf16 v[86:89], v[146:149], v[194:197], v[86:89]
	s_setprio 0
	s_cmp_eq_u32 s45, 12
	s_cbranch_scc1 .Lhu_k3_x0
	s_waitcnt vmcnt(6)
	s_branch .Lhu_k3_cb

.Lhu_k3_cb:
	s_barrier
	s_add_i32 s45, s45, 3
	s_cmp_lt_u32 s45, 15
	s_cbranch_scc1 .Lhu_loop
	ds_read_b128 v[150:153], v248
	ds_read_b128 v[154:157], v248 offset:1024
	ds_read_b128 v[158:161], v248 offset:2048
	ds_read_b128 v[162:165], v248 offset:3072
	ds_read_b128 v[134:137], v249
	ds_read_b128 v[138:141], v249 offset:1024
	ds_read_b128 v[142:145], v249 offset:2048
	ds_read_b128 v[146:149], v249 offset:3072
	ds_read_b128 v[166:169], v250
	ds_read_b128 v[170:173], v250 offset:1024
	ds_read_b128 v[174:177], v250 offset:2048
	ds_read_b128 v[178:181], v250 offset:3072
	ds_read_b128 v[182:185], v250 offset:4096
	ds_read_b128 v[186:189], v250 offset:5120
	ds_read_b128 v[190:193], v250 offset:6144
	ds_read_b128 v[194:197], v250 offset:7168
	s_and_b64 vcc, exec, s[14:15]
	s_cbranch_vccz .Lhu_k4_y
	s_branch .Lhu_k4_bar

.Lhu_k4_bar:
	s_waitcnt lgkmcnt(0)
	s_barrier
	s_and_b64 vcc, exec, s[14:15]
	s_cbranch_vccnz .Lhu_k4_x
.Lhu_k4_ym:
	s_setprio 1
	v_mfma_f32_16x16x32_bf16 v[102:105], v[150:153], v[166:169], v[102:105]
	v_mfma_f32_16x16x32_bf16 v[70:73], v[158:161], v[166:169], v[70:73]
	v_mfma_f32_16x16x32_bf16 v[114:117], v[150:153], v[174:177], v[114:117]
	v_mfma_f32_16x16x32_bf16 v[82:85], v[158:161], v[174:177], v[82:85]
	v_mfma_f32_16x16x32_bf16 v[110:113], v[150:153], v[182:185], v[110:113]
	v_mfma_f32_16x16x32_bf16 v[78:81], v[158:161], v[182:185], v[78:81]
	v_mfma_f32_16x16x32_bf16 v[106:109], v[150:153], v[190:193], v[106:109]
	v_mfma_f32_16x16x32_bf16 v[74:77], v[158:161], v[190:193], v[74:77]
	v_mfma_f32_16x16x32_bf16 v[102:105], v[154:157], v[170:173], v[102:105]
	v_mfma_f32_16x16x32_bf16 v[70:73], v[162:165], v[170:173], v[70:73]
	v_mfma_f32_16x16x32_bf16 v[114:117], v[154:157], v[178:181], v[114:117]
	v_mfma_f32_16x16x32_bf16 v[82:85], v[162:165], v[178:181], v[82:85]
	v_mfma_f32_16x16x32_bf16 v[110:113], v[154:157], v[186:189], v[110:113]
	v_mfma_f32_16x16x32_bf16 v[78:81], v[162:165], v[186:189], v[78:81]
	v_mfma_f32_16x16x32_bf16 v[106:109], v[154:157], v[194:197], v[106:109]
	v_mfma_f32_16x16x32_bf16 v[74:77], v[162:165], v[194:197], v[74:77]
	s_setprio 0
	s_setprio 1
	v_mfma_f32_16x16x32_bf16 v[130:133], v[134:137], v[166:169], v[130:133]
	v_mfma_f32_16x16x32_bf16 v[98:101], v[142:145], v[166:169], v[98:101]
	v_mfma_f32_16x16x32_bf16 v[126:129], v[134:137], v[174:177], v[126:129]
	v_mfma_f32_16x16x32_bf16 v[94:97], v[142:145], v[174:177], v[94:97]
	v_mfma_f32_16x16x32_bf16 v[122:125], v[134:137], v[182:185], v[122:125]
	v_mfma_f32_16x16x32_bf16 v[90:93], v[142:145], v[182:185], v[90:93]
	v_mfma_f32_16x16x32_bf16 v[118:121], v[134:137], v[190:193], v[118:121]
	v_mfma_f32_16x16x32_bf16 v[86:89], v[142:145], v[190:193], v[86:89]
	v_mfma_f32_16x16x32_bf16 v[130:133], v[138:141], v[170:173], v[130:133]
	v_mfma_f32_16x16x32_bf16 v[98:101], v[146:149], v[170:173], v[98:101]
	v_mfma_f32_16x16x32_bf16 v[126:129], v[138:141], v[178:181], v[126:129]
	v_mfma_f32_16x16x32_bf16 v[94:97], v[146:149], v[178:181], v[94:97]
	v_mfma_f32_16x16x32_bf16 v[122:125], v[138:141], v[186:189], v[122:125]
	v_mfma_f32_16x16x32_bf16 v[90:93], v[146:149], v[186:189], v[90:93]
	v_mfma_f32_16x16x32_bf16 v[118:121], v[138:141], v[194:197], v[118:121]
	v_mfma_f32_16x16x32_bf16 v[86:89], v[146:149], v[194:197], v[86:89]
	s_setprio 0
	s_branch .Lhu_k4_cb

.Lhu_k4_cb:
	s_barrier
	s_mov_b64 s[0:1], -1
	s_branch .LBB0_122
